# scan workgroup publishes its queue-A release flag at the start of its last chunk so the idle partner wakes before the phase ends, on v41
# baseline (speedup 1.0000x reference)
.Lch_last:
	v_mov_b64_e32 v[84:85], v[104:105]
	v_mov_b64_e32 v[68:69], v[88:89]
	v_mov_b64_e32 v[72:73], v[96:97]
	v_mov_b64_e32 v[76:77], v[108:109]
	v_mov_b64_e32 v[80:81], v[112:113]
	v_mov_b64_e32 v[86:87], v[106:107]
	v_mov_b64_e32 v[70:71], v[90:91]
	v_mov_b64_e32 v[74:75], v[98:99]
	v_mov_b64_e32 v[78:79], v[110:111]
	v_mov_b64_e32 v[82:83], v[114:115]
	v_cmp_eq_u32_e32 vcc, 0, v254
	s_and_saveexec_b64 s[16:17], vcc
	s_cbranch_execz .Lch_pubdone
	s_getreg_b32 s14, hwreg(HW_REG_HW_ID)
	s_getreg_b32 s15, hwreg(HW_REG_XCC_ID, 0, 4)
	s_bfe_u32 s14, s14, 0x80008
	s_lshl_b32 s15, s15, 8
	s_and_b32 s15, s15, 0xf00
	s_or_b32 s14, s14, s15
	s_lshl_b32 s14, s14, 2
	s_lshl_b32 s15, s82, 14
	s_add_i32 s14, s14, s15
	s_lshl_b32 s15, s82, 3
	s_sub_i32 s14, s14, s15
	s_sub_i32 s14, s14, 0xe000
	s_ashr_i32 s15, s14, 31
	s_add_u32 s14, s90, s14
	s_addc_u32 s15, s91, s15
	v_mov_b32_e32 v250, 0x1000000
	global_atomic_add v149, v250, s[14:15]
.Lch_pubdone:
	s_or_b64 exec, exec, s[16:17]
	s_branch .LBB0_490
.LBB0_496:
	s_mov_b64 s[6:7], 0
	s_mov_b64 s[4:5], -1
	s_movk_i32 s89, 0x1800
	v_readlane_b32 s90, v255, 25
	v_readlane_b32 s91, v255, 26
	s_movk_i32 s92, 0x300
	s_movk_i32 s93, 0x104
	s_movk_i32 s96, 0x2b8
	s_movk_i32 s97, 0x15c0
	v_readlane_b32 s2, v255, 28
